# combo2 + NSA near-path lookups batched + top-k rounds via max3 tree and eq-compare select
# baseline (speedup 1.0000x reference)
.LBB0_737:
	s_or_b64 exec, exec, s[2:3]
	v_and_b32_e32 v3, 3, v2
	v_cmp_eq_u32_e32 vcc, v3, v99
	v_ashrrev_i32_e32 v3, 2, v2
	s_add_i32 s42, s42, -1
	v_cndmask_b32_e32 v3, -1, v3, vcc
	v_cmp_eq_u32_e64 s[38:39], 0, v3
	v_cmp_eq_u32_e64 s[40:41], 1, v3
	v_cmp_eq_u32_e64 s[4:5], 2, v3
	v_cndmask_b32_e64 v100, v100, v192, s[38:39]
	v_cmp_eq_u32_e32 vcc, 3, v3
	v_cndmask_b32_e64 v101, v101, v192, s[40:41]
	v_cmp_eq_u32_e64 s[38:39], 4, v3
	v_cndmask_b32_e64 v102, v102, v192, s[4:5]
	v_cmp_eq_u32_e64 s[40:41], 5, v3
	v_cndmask_b32_e32 v103, v103, v192, vcc
	v_cmp_eq_u32_e64 s[4:5], 6, v3
	v_cndmask_b32_e64 v104, v104, v192, s[38:39]
	v_cmp_eq_u32_e32 vcc, 7, v3
	v_cndmask_b32_e64 v105, v105, v192, s[40:41]
	v_cmp_eq_u32_e64 s[38:39], 8, v3
	v_cndmask_b32_e64 v106, v106, v192, s[4:5]
	v_cmp_eq_u32_e64 s[40:41], 9, v3
	v_cndmask_b32_e32 v107, v107, v192, vcc
	v_cmp_eq_u32_e64 s[4:5], 10, v3
	v_cndmask_b32_e64 v108, v108, v192, s[38:39]
	v_cmp_eq_u32_e32 vcc, 11, v3
	v_cndmask_b32_e64 v109, v109, v192, s[40:41]
	v_cmp_eq_u32_e64 s[38:39], 12, v3
	v_cndmask_b32_e64 v110, v110, v192, s[4:5]
	v_cmp_eq_u32_e64 s[40:41], 13, v3
	v_cndmask_b32_e32 v111, v111, v192, vcc
	v_cmp_eq_u32_e64 s[4:5], 14, v3
	v_cndmask_b32_e64 v112, v112, v192, s[38:39]
	v_cmp_eq_u32_e32 vcc, 15, v3
	v_cndmask_b32_e64 v113, v113, v192, s[40:41]
	v_cmp_eq_u32_e64 s[38:39], 16, v3
	v_cndmask_b32_e64 v114, v114, v192, s[4:5]
	v_cmp_eq_u32_e64 s[40:41], 17, v3
	v_cndmask_b32_e32 v115, v115, v192, vcc
	v_cmp_eq_u32_e64 s[4:5], 18, v3
	v_cndmask_b32_e64 v116, v116, v192, s[38:39]
	v_cmp_eq_u32_e32 vcc, 19, v3
	v_cndmask_b32_e64 v117, v117, v192, s[40:41]
	v_cmp_eq_u32_e64 s[38:39], 20, v3
	v_cndmask_b32_e64 v118, v118, v192, s[4:5]
	v_cmp_eq_u32_e64 s[40:41], 21, v3
	v_cndmask_b32_e32 v119, v119, v192, vcc
	v_cmp_eq_u32_e64 s[4:5], 22, v3
	v_cndmask_b32_e64 v120, v120, v192, s[38:39]
	v_cmp_eq_u32_e32 vcc, 23, v3
	v_cndmask_b32_e64 v121, v121, v192, s[40:41]
	v_cmp_eq_u32_e64 s[38:39], 24, v3
	v_cndmask_b32_e64 v122, v122, v192, s[4:5]
	v_cmp_eq_u32_e64 s[40:41], 25, v3
	v_cndmask_b32_e32 v123, v123, v192, vcc
	v_cmp_eq_u32_e64 s[4:5], 26, v3
	v_cndmask_b32_e64 v124, v124, v192, s[38:39]
	v_cmp_eq_u32_e32 vcc, 27, v3
	v_cndmask_b32_e64 v125, v125, v192, s[40:41]
	v_cmp_eq_u32_e64 s[38:39], 28, v3
	v_cndmask_b32_e64 v127, v127, v192, s[4:5]
	v_cmp_eq_u32_e64 s[40:41], 29, v3
	v_cndmask_b32_e32 v128, v128, v192, vcc
	v_cmp_eq_u32_e64 s[4:5], 30, v3
	v_cndmask_b32_e64 v129, v129, v192, s[38:39]
	v_cmp_eq_u32_e32 vcc, 31, v3
	v_cndmask_b32_e64 v130, v130, v192, s[40:41]
	v_cmp_eq_u32_e64 s[38:39], 32, v3
	v_cndmask_b32_e64 v131, v131, v192, s[4:5]
	v_cmp_eq_u32_e64 s[40:41], 33, v3
	v_cndmask_b32_e32 v132, v132, v192, vcc
	v_cmp_eq_u32_e64 s[4:5], 34, v3
	v_cndmask_b32_e64 v133, v133, v192, s[38:39]
	v_cmp_eq_u32_e32 vcc, 35, v3
	v_cndmask_b32_e64 v134, v134, v192, s[40:41]
	v_cmp_eq_u32_e64 s[38:39], 36, v3
	v_cndmask_b32_e64 v135, v135, v192, s[4:5]
	v_cmp_eq_u32_e64 s[40:41], 37, v3
	v_cndmask_b32_e32 v136, v136, v192, vcc
	v_cmp_eq_u32_e64 s[4:5], 38, v3
	v_cndmask_b32_e64 v137, v137, v192, s[38:39]
	v_cmp_eq_u32_e32 vcc, 39, v3
	v_cndmask_b32_e64 v138, v138, v192, s[40:41]
	v_cmp_eq_u32_e64 s[38:39], 40, v3
	v_cndmask_b32_e64 v139, v139, v192, s[4:5]
	v_cmp_eq_u32_e64 s[40:41], 41, v3
	v_cndmask_b32_e32 v140, v140, v192, vcc
	v_cmp_eq_u32_e64 s[4:5], 42, v3
	v_cndmask_b32_e64 v141, v141, v192, s[38:39]
	v_cmp_eq_u32_e32 vcc, 43, v3
	v_cndmask_b32_e64 v142, v142, v192, s[40:41]
	v_cmp_eq_u32_e64 s[38:39], 44, v3
	v_cndmask_b32_e64 v143, v143, v192, s[4:5]
	v_cmp_eq_u32_e64 s[40:41], 45, v3
	v_cndmask_b32_e32 v144, v144, v192, vcc
	v_cmp_eq_u32_e64 s[4:5], 46, v3
	v_cndmask_b32_e64 v145, v145, v192, s[38:39]
	v_cmp_eq_u32_e32 vcc, 47, v3
	v_cndmask_b32_e64 v146, v146, v192, s[40:41]
	v_cmp_eq_u32_e64 s[38:39], 48, v3
	v_cndmask_b32_e64 v147, v147, v192, s[4:5]
	v_cmp_eq_u32_e64 s[40:41], 49, v3
	v_cndmask_b32_e32 v148, v148, v192, vcc
	v_cmp_eq_u32_e64 s[4:5], 50, v3
	v_cndmask_b32_e64 v149, v149, v192, s[38:39]
	v_cmp_eq_u32_e32 vcc, 51, v3
	v_cndmask_b32_e64 v150, v150, v192, s[40:41]
	v_cmp_eq_u32_e64 s[38:39], 52, v3
	v_cndmask_b32_e64 v151, v151, v192, s[4:5]
	v_cmp_eq_u32_e64 s[40:41], 53, v3
	v_cndmask_b32_e32 v160, v160, v192, vcc
	v_cmp_eq_u32_e64 s[4:5], 54, v3
	v_cndmask_b32_e64 v161, v161, v192, s[38:39]
	v_cmp_eq_u32_e32 vcc, 55, v3
	v_cndmask_b32_e64 v162, v162, v192, s[40:41]
	v_cmp_eq_u32_e64 s[38:39], 56, v3
	v_cndmask_b32_e64 v163, v163, v192, s[4:5]
	v_cmp_eq_u32_e64 s[40:41], 57, v3
	v_cndmask_b32_e32 v164, v164, v192, vcc
	v_cmp_eq_u32_e64 s[4:5], 58, v3
	v_cndmask_b32_e64 v165, v165, v192, s[38:39]
	v_cmp_eq_u32_e32 vcc, 59, v3
	v_cndmask_b32_e64 v166, v166, v192, s[40:41]
	v_cmp_eq_u32_e64 s[38:39], 60, v3
	v_cndmask_b32_e64 v167, v167, v192, s[4:5]
	v_cmp_eq_u32_e64 s[40:41], 61, v3
	v_cndmask_b32_e32 v168, v168, v192, vcc
	v_cmp_eq_u32_e64 s[4:5], 62, v3
	v_cndmask_b32_e64 v169, v169, v192, s[38:39]
	v_cmp_eq_u32_e32 vcc, 63, v3
	v_cndmask_b32_e64 v170, v170, v192, s[40:41]
	v_cndmask_b32_e64 v171, v171, v192, s[4:5]
	v_cndmask_b32_e32 v126, v126, v192, vcc
	s_cmp_eq_u32 s42, 0
	s_cbranch_scc1 .LBB0_747
.LBB0_738:
	v_max3_f32 v3, v100, v101, v102
	v_max3_f32 v4, v103, v104, v105
	v_max3_f32 v3, v3, v106, v107
	v_max3_f32 v4, v4, v108, v109
	v_max3_f32 v3, v3, v110, v111
	v_max3_f32 v4, v4, v112, v113
	v_max3_f32 v3, v3, v114, v115
	v_max3_f32 v4, v4, v116, v117
	v_max3_f32 v3, v3, v118, v119
	v_max3_f32 v4, v4, v120, v121
	v_max3_f32 v3, v3, v122, v123
	v_max3_f32 v4, v4, v124, v125
	v_max3_f32 v3, v3, v127, v128
	v_max3_f32 v4, v4, v129, v130
	v_max3_f32 v3, v3, v131, v132
	v_max3_f32 v4, v4, v133, v134
	v_max3_f32 v3, v3, v135, v136
	v_max3_f32 v4, v4, v137, v138
	v_max3_f32 v3, v3, v139, v140
	v_max3_f32 v4, v4, v141, v142
	v_max3_f32 v3, v3, v143, v144
	v_max3_f32 v4, v4, v145, v146
	v_max3_f32 v3, v3, v147, v148
	v_max3_f32 v4, v4, v149, v150
	v_max3_f32 v3, v3, v151, v160
	v_max3_f32 v4, v4, v161, v162
	v_max3_f32 v3, v3, v163, v164
	v_max3_f32 v4, v4, v165, v166
	v_max3_f32 v3, v3, v167, v168
	v_max3_f32 v4, v4, v169, v170
	v_max3_f32 v3, v3, v171, v126
	v_max_f32_e32 v3, v3, v4
	v_mov_b32_e32 v2, 0x40000
	v_cmp_eq_f32_e64 s[38:39], v126, v3
	v_cmp_eq_f32_e64 s[40:41], v171, v3
	v_cmp_eq_f32_e64 s[2:3], v170, v3
	v_cndmask_b32_e64 v2, v2, 63, s[38:39]
	v_cmp_eq_f32_e64 s[4:5], v169, v3
	v_cndmask_b32_e64 v2, v2, 62, s[40:41]
	v_cmp_eq_f32_e64 s[38:39], v168, v3
	v_cndmask_b32_e64 v2, v2, 61, s[2:3]
	v_cmp_eq_f32_e64 s[40:41], v167, v3
	v_cndmask_b32_e64 v2, v2, 60, s[4:5]
	v_cmp_eq_f32_e64 s[2:3], v166, v3
	v_cndmask_b32_e64 v2, v2, 59, s[38:39]
	v_cmp_eq_f32_e64 s[4:5], v165, v3
	v_cndmask_b32_e64 v2, v2, 58, s[40:41]
	v_cmp_eq_f32_e64 s[38:39], v164, v3
	v_cndmask_b32_e64 v2, v2, 57, s[2:3]
	v_cmp_eq_f32_e64 s[40:41], v163, v3
	v_cndmask_b32_e64 v2, v2, 56, s[4:5]
	v_cmp_eq_f32_e64 s[2:3], v162, v3
	v_cndmask_b32_e64 v2, v2, 55, s[38:39]
	v_cmp_eq_f32_e64 s[4:5], v161, v3
	v_cndmask_b32_e64 v2, v2, 54, s[40:41]
	v_cmp_eq_f32_e64 s[38:39], v160, v3
	v_cndmask_b32_e64 v2, v2, 53, s[2:3]
	v_cmp_eq_f32_e64 s[40:41], v151, v3
	v_cndmask_b32_e64 v2, v2, 52, s[4:5]
	v_cmp_eq_f32_e64 s[2:3], v150, v3
	v_cndmask_b32_e64 v2, v2, 51, s[38:39]
	v_cmp_eq_f32_e64 s[4:5], v149, v3
	v_cndmask_b32_e64 v2, v2, 50, s[40:41]
	v_cmp_eq_f32_e64 s[38:39], v148, v3
	v_cndmask_b32_e64 v2, v2, 49, s[2:3]
	v_cmp_eq_f32_e64 s[40:41], v147, v3
	v_cndmask_b32_e64 v2, v2, 48, s[4:5]
	v_cmp_eq_f32_e64 s[2:3], v146, v3
	v_cndmask_b32_e64 v2, v2, 47, s[38:39]
	v_cmp_eq_f32_e64 s[4:5], v145, v3
	v_cndmask_b32_e64 v2, v2, 46, s[40:41]
	v_cmp_eq_f32_e64 s[38:39], v144, v3
	v_cndmask_b32_e64 v2, v2, 45, s[2:3]
	v_cmp_eq_f32_e64 s[40:41], v143, v3
	v_cndmask_b32_e64 v2, v2, 44, s[4:5]
	v_cmp_eq_f32_e64 s[2:3], v142, v3
	v_cndmask_b32_e64 v2, v2, 43, s[38:39]
	v_cmp_eq_f32_e64 s[4:5], v141, v3
	v_cndmask_b32_e64 v2, v2, 42, s[40:41]
	v_cmp_eq_f32_e64 s[38:39], v140, v3
	v_cndmask_b32_e64 v2, v2, 41, s[2:3]
	v_cmp_eq_f32_e64 s[40:41], v139, v3
	v_cndmask_b32_e64 v2, v2, 40, s[4:5]
	v_cmp_eq_f32_e64 s[2:3], v138, v3
	v_cndmask_b32_e64 v2, v2, 39, s[38:39]
	v_cmp_eq_f32_e64 s[4:5], v137, v3
	v_cndmask_b32_e64 v2, v2, 38, s[40:41]
	v_cmp_eq_f32_e64 s[38:39], v136, v3
	v_cndmask_b32_e64 v2, v2, 37, s[2:3]
	v_cmp_eq_f32_e64 s[40:41], v135, v3
	v_cndmask_b32_e64 v2, v2, 36, s[4:5]
	v_cmp_eq_f32_e64 s[2:3], v134, v3
	v_cndmask_b32_e64 v2, v2, 35, s[38:39]
	v_cmp_eq_f32_e64 s[4:5], v133, v3
	v_cndmask_b32_e64 v2, v2, 34, s[40:41]
	v_cmp_eq_f32_e64 s[38:39], v132, v3
	v_cndmask_b32_e64 v2, v2, 33, s[2:3]
	v_cmp_eq_f32_e64 s[40:41], v131, v3
	v_cndmask_b32_e64 v2, v2, 32, s[4:5]
	v_cmp_eq_f32_e64 s[2:3], v130, v3
	v_cndmask_b32_e64 v2, v2, 31, s[38:39]
	v_cmp_eq_f32_e64 s[4:5], v129, v3
	v_cndmask_b32_e64 v2, v2, 30, s[40:41]
	v_cmp_eq_f32_e64 s[38:39], v128, v3
	v_cndmask_b32_e64 v2, v2, 29, s[2:3]
	v_cmp_eq_f32_e64 s[40:41], v127, v3
	v_cndmask_b32_e64 v2, v2, 28, s[4:5]
	v_cmp_eq_f32_e64 s[2:3], v125, v3
	v_cndmask_b32_e64 v2, v2, 27, s[38:39]
	v_cmp_eq_f32_e64 s[4:5], v124, v3
	v_cndmask_b32_e64 v2, v2, 26, s[40:41]
	v_cmp_eq_f32_e64 s[38:39], v123, v3
	v_cndmask_b32_e64 v2, v2, 25, s[2:3]
	v_cmp_eq_f32_e64 s[40:41], v122, v3
	v_cndmask_b32_e64 v2, v2, 24, s[4:5]
	v_cmp_eq_f32_e64 s[2:3], v121, v3
	v_cndmask_b32_e64 v2, v2, 23, s[38:39]
	v_cmp_eq_f32_e64 s[4:5], v120, v3
	v_cndmask_b32_e64 v2, v2, 22, s[40:41]
	v_cmp_eq_f32_e64 s[38:39], v119, v3
	v_cndmask_b32_e64 v2, v2, 21, s[2:3]
	v_cmp_eq_f32_e64 s[40:41], v118, v3
	v_cndmask_b32_e64 v2, v2, 20, s[4:5]
	v_cmp_eq_f32_e64 s[2:3], v117, v3
	v_cndmask_b32_e64 v2, v2, 19, s[38:39]
	v_cmp_eq_f32_e64 s[4:5], v116, v3
	v_cndmask_b32_e64 v2, v2, 18, s[40:41]
	v_cmp_eq_f32_e64 s[38:39], v115, v3
	v_cndmask_b32_e64 v2, v2, 17, s[2:3]
	v_cmp_eq_f32_e64 s[40:41], v114, v3
	v_cndmask_b32_e64 v2, v2, 16, s[4:5]
	v_cmp_eq_f32_e64 s[2:3], v113, v3
	v_cndmask_b32_e64 v2, v2, 15, s[38:39]
	v_cmp_eq_f32_e64 s[4:5], v112, v3
	v_cndmask_b32_e64 v2, v2, 14, s[40:41]
	v_cmp_eq_f32_e64 s[38:39], v111, v3
	v_cndmask_b32_e64 v2, v2, 13, s[2:3]
	v_cmp_eq_f32_e64 s[40:41], v110, v3
	v_cndmask_b32_e64 v2, v2, 12, s[4:5]
	v_cmp_eq_f32_e64 s[2:3], v109, v3
	v_cndmask_b32_e64 v2, v2, 11, s[38:39]
	v_cmp_eq_f32_e64 s[4:5], v108, v3
	v_cndmask_b32_e64 v2, v2, 10, s[40:41]
	v_cmp_eq_f32_e64 s[38:39], v107, v3
	v_cndmask_b32_e64 v2, v2, 9, s[2:3]
	v_cmp_eq_f32_e64 s[40:41], v106, v3
	v_cndmask_b32_e64 v2, v2, 8, s[4:5]
	v_cmp_eq_f32_e64 s[2:3], v105, v3
	v_cndmask_b32_e64 v2, v2, 7, s[38:39]
	v_cmp_eq_f32_e64 s[4:5], v104, v3
	v_cndmask_b32_e64 v2, v2, 6, s[40:41]
	v_cmp_eq_f32_e64 s[38:39], v103, v3
	v_cndmask_b32_e64 v2, v2, 5, s[2:3]
	v_cmp_eq_f32_e64 s[40:41], v102, v3
	v_cndmask_b32_e64 v2, v2, 4, s[4:5]
	v_cmp_eq_f32_e64 s[2:3], v101, v3
	v_cndmask_b32_e64 v2, v2, 3, s[38:39]
	v_cmp_eq_f32_e64 s[4:5], v100, v3
	v_cndmask_b32_e64 v2, v2, 2, s[40:41]
	v_cndmask_b32_e64 v2, v2, 1, s[2:3]
	v_cndmask_b32_e64 v2, v2, 0, s[4:5]
	v_lshlrev_b32_e32 v2, 2, v2
	ds_swizzle_b32 v4, v3 offset:swizzle(SWAP,16)
	v_add_u32_e32 v2, v2, v99
	ds_swizzle_b32 v5, v2 offset:swizzle(SWAP,16)
	s_waitcnt lgkmcnt(1)
	v_cmp_lt_f32_e64 s[2:3], v3, v4
	v_cmp_nlt_f32_e32 vcc, v3, v4
	s_and_saveexec_b64 s[4:5], vcc
	s_cbranch_execz .LBB0_740
	v_cmp_eq_f32_e32 vcc, v3, v4
	s_waitcnt lgkmcnt(0)
	v_cmp_lt_i32_e64 s[38:39], v5, v2
	s_and_b64 s[38:39], vcc, s[38:39]
	s_andn2_b64 s[2:3], s[2:3], exec
	s_and_b64 s[38:39], s[38:39], exec
	s_or_b64 s[2:3], s[2:3], s[38:39]
